# v7 + intra-CU half stagger: waves 4-7 sleep ~640 cycles at each FFT stage entry so SIMD partners do not run ds_read/MFMA bursts in lockstep
# baseline (speedup 1.0000x reference)
.LBB0_549:
	s_ashr_i32 s49, s48, 31
	s_lshl_b64 s[20:21], s[48:49], 1
	s_add_u32 s20, s42, s20
	s_addc_u32 s21, s43, s21
	v_add3_u32 v20, v20, v145, s1
	v_mov_b64_e32 v[78:79], s[20:21]
	v_mad_i64_i32 v[20:21], s[20:21], v20, s8, v[78:79]
	v_lshlrev_b32_e32 v0, 1, v0
	v_lshl_add_u64 v[20:21], v[20:21], 0, v[0:1]
	v_add3_u32 v0, v19, v149, s1
	v_mad_i64_i32 v[22:23], s[20:21], v0, s8, v[78:79]
	v_lshlrev_b32_e32 v0, 1, v18
	v_lshl_add_u64 v[18:19], v[22:23], 0, v[0:1]
	v_add3_u32 v0, v61, v153, s1
	v_mad_i64_i32 v[62:63], s[20:21], v0, s8, v[78:79]
	v_lshlrev_b32_e32 v0, 1, v60
	v_lshl_add_u64 v[60:61], v[62:63], 0, v[0:1]
	v_add3_u32 v0, v59, v157, s1
	v_mad_i64_i32 v[62:63], s[20:21], v0, s8, v[78:79]
	v_lshlrev_b32_e32 v0, 1, v58
	v_lshl_add_u64 v[58:59], v[62:63], 0, v[0:1]
	v_add3_u32 v0, v69, v161, s1
	v_mad_i64_i32 v[70:71], s[20:21], v0, s8, v[78:79]
	v_lshlrev_b32_e32 v0, 1, v68
	v_lshl_add_u64 v[68:69], v[70:71], 0, v[0:1]
	v_add3_u32 v0, v67, v165, s1
	v_mad_i64_i32 v[70:71], s[20:21], v0, s8, v[78:79]
	v_lshlrev_b32_e32 v0, 1, v66
	v_lshl_add_u64 v[66:67], v[70:71], 0, v[0:1]
	v_add3_u32 v0, v77, v169, s1
	v_mad_i64_i32 v[80:81], s[20:21], v0, s8, v[78:79]
	v_lshlrev_b32_e32 v0, 1, v76
	v_lshl_add_u64 v[76:77], v[80:81], 0, v[0:1]
	v_add3_u32 v0, v75, v173, s1
	v_mad_i64_i32 v[78:79], s[20:21], v0, s8, v[78:79]
	v_lshlrev_b32_e32 v0, 1, v74
	v_mov_b32_e32 v111, v1
	v_lshl_add_u64 v[74:75], v[78:79], 0, v[0:1]
	v_lshl_add_u64 v[20:21], v[20:21], 0, v[110:111]
	v_lshl_add_u64 v[18:19], v[18:19], 0, v[110:111]
	v_lshl_add_u64 v[60:61], v[60:61], 0, v[110:111]
	v_lshl_add_u64 v[58:59], v[58:59], 0, v[110:111]
	v_lshl_add_u64 v[68:69], v[68:69], 0, v[110:111]
	v_lshl_add_u64 v[66:67], v[66:67], 0, v[110:111]
	v_lshl_add_u64 v[76:77], v[76:77], 0, v[110:111]
	v_lshl_add_u64 v[74:75], v[74:75], 0, v[110:111]
	s_mov_b64 s[48:49], -1
	s_and_b64 vcc, exec, s[16:17]
	s_cbranch_vccz .LBB0_553
	s_cmp_lt_u32 s71, 4
	s_cbranch_scc1 .Lfs_s1s
	s_sleep 10
.Lfs_s1s:
	global_load_dwordx4 v[82:85], v[92:93], off
	global_load_dwordx4 v[86:89], v[96:97], off
	s_mov_b32 s1, 1
	v_mov_b32_e32 v120, v182
	v_mov_b32_e32 v0, v181
	v_mov_b32_e32 v111, v180
	s_waitcnt vmcnt(5)
	v_mov_b64_e32 v[126:127], v[118:119]
	s_waitcnt vmcnt(4)
	v_mov_b64_e32 v[124:125], v[112:113]
	s_waitcnt vmcnt(3)
	v_mov_b64_e32 v[122:123], v[116:117]
	s_waitcnt vmcnt(2)
	v_mov_b64_e32 v[128:129], v[114:115]

.LBB0_553:
	s_and_b64 vcc, exec, s[48:49]
	s_cbranch_vccz .LBB0_556
	s_cmp_lt_u32 s71, 4
	s_cbranch_scc1 .Lfs_s1b
	s_sleep 10
.Lfs_s1b:
	s_mov_b32 s1, 1
	s_mov_b32 s20, 0
	v_mov_b32_e32 v0, v180
	v_mov_b32_e32 v84, v183

.LBB0_556:
	s_mov_b32 s1, 0
	s_waitcnt lgkmcnt(0)
	s_barrier
	global_load_dwordx4 v[22:25], v[20:21], off
	s_nop 0
	global_load_dwordx4 v[18:21], v[18:19], off
	s_nop 0
	global_load_dwordx4 v[62:65], v[60:61], off
	s_nop 0
	global_load_dwordx4 v[58:61], v[58:59], off
	s_nop 0
	global_load_dwordx4 v[70:73], v[68:69], off
	s_nop 0
	global_load_dwordx4 v[66:69], v[66:67], off
	s_nop 0
	global_load_dwordx4 v[78:81], v[76:77], off
	s_nop 0
	global_load_dwordx4 v[74:77], v[74:75], off
	s_cmp_lt_u32 s71, 4
	s_cbranch_scc1 .Lfs_s2
	s_sleep 10
.Lfs_s2:
.LBB0_557:
	v_add_u32_e32 v0, s1, v185
	v_add_u32_e32 v82, 0x11000, v0
	v_add_u32_e32 v84, 0x11440, v0
	v_add_u32_e32 v86, 0x19800, v0
	v_add_u32_e32 v88, 0x19c40, v0
	ds_read_b64_tr_b16 v[82:83], v82
	ds_read_b64_tr_b16 v[84:85], v84
	ds_read_b64_tr_b16 v[86:87], v86
	ds_read_b64_tr_b16 v[88:89], v88
	s_waitcnt lgkmcnt(2)
	v_mfma_f32_16x16x32_f16 v[82:85], v[54:57], v[82:85], 0
	s_waitcnt vmcnt(9)
	v_add_u32_e32 v112, 0x13200, v0
	ds_read_b64_tr_b16 v[112:113], v112
	s_waitcnt vmcnt(8)
	v_add_u32_e32 v114, 0x13640, v0
	s_waitcnt lgkmcnt(1)
	v_mfma_f32_16x16x32_f16 v[82:85], v[50:53], v[86:89], v[82:85]
	v_add_u32_e32 v116, 0x1ba00, v0
	v_add_u32_e32 v117, 0x1be40, v0
	ds_read_b64_tr_b16 v[114:115], v114
	ds_read_b64_tr_b16 v[86:87], v116
	ds_read_b64_tr_b16 v[88:89], v117
	s_waitcnt lgkmcnt(2)
	v_mfma_f32_16x16x32_f16 v[82:85], v[46:49], v[112:115], v[82:85]
	v_add_u32_e32 v118, 0x15400, v0
	ds_read_b64_tr_b16 v[112:113], v118
	v_add_u32_e32 v119, 0x15840, v0
	s_waitcnt lgkmcnt(1)
	v_mfma_f32_16x16x32_f16 v[82:85], v[42:45], v[86:89], v[82:85]
	v_add_u32_e32 v120, 0x1dc00, v0
	v_add_u32_e32 v121, 0x1e040, v0
	ds_read_b64_tr_b16 v[114:115], v119
	ds_read_b64_tr_b16 v[86:87], v120
	ds_read_b64_tr_b16 v[88:89], v121
	s_waitcnt lgkmcnt(2)
	v_mfma_f32_16x16x32_f16 v[82:85], v[38:41], v[112:115], v[82:85]
	v_add_u32_e32 v122, 0x17600, v0
	ds_read_b64_tr_b16 v[112:113], v122
	v_add_u32_e32 v123, 0x17a40, v0
	s_waitcnt lgkmcnt(1)
	v_mfma_f32_16x16x32_f16 v[82:85], v[34:37], v[86:89], v[82:85]
	v_add_u32_e32 v124, 0x1fe00, v0
	v_add_u32_e32 v125, 0x20240, v0
	ds_read_b64_tr_b16 v[114:115], v123
	ds_read_b64_tr_b16 v[86:87], v124
	ds_read_b64_tr_b16 v[88:89], v125
	s_waitcnt lgkmcnt(2)
	v_mfma_f32_16x16x32_f16 v[82:85], v[30:33], v[112:115], v[82:85]
	v_add_u32_e32 v111, s1, v193
	v_add_u32_e32 v126, 0x11020, v0
	v_add_u32_e32 v127, 0x11460, v0
	s_waitcnt lgkmcnt(0)
	v_mfma_f32_16x16x32_f16 v[82:85], v[26:29], v[86:89], v[82:85]
	v_add_u32_e32 v128, 0x19820, v0
	v_add_u32_e32 v116, 0x19c60, v0
	v_add_u32_e32 v117, 0x13220, v0
	v_add_u32_e32 v118, 0x13660, v0
	v_add_u32_e32 v119, 0x1ba20, v0
	s_nop 2
	v_cvt_f16_f32_e32 v82, v82
	v_cvt_f16_f32_e32 v83, v83
	v_cvt_f16_f32_e32 v84, v84
	v_cvt_f16_f32_e32 v85, v85
	ds_write_b16 v111, v82
	ds_write_b16 v111, v83 offset:256
	ds_write_b16 v111, v84 offset:512
	ds_write_b16 v111, v85 offset:768
	ds_read_b64_tr_b16 v[82:83], v126
	ds_read_b64_tr_b16 v[84:85], v127
	ds_read_b64_tr_b16 v[86:87], v128
	ds_read_b64_tr_b16 v[88:89], v116
	s_waitcnt lgkmcnt(2)
	v_mfma_f32_16x16x32_f16 v[82:85], v[54:57], v[82:85], 0
	ds_read_b64_tr_b16 v[112:113], v117
	v_add_u32_e32 v120, 0x1be60, v0
	v_add_u32_e32 v121, 0x15420, v0
	s_waitcnt lgkmcnt(1)
	v_mfma_f32_16x16x32_f16 v[82:85], v[50:53], v[86:89], v[82:85]
	ds_read_b64_tr_b16 v[114:115], v118
	ds_read_b64_tr_b16 v[86:87], v119
	ds_read_b64_tr_b16 v[88:89], v120
	v_add_u32_e32 v122, 0x15860, v0
	v_add_u32_e32 v116, 0x1dc20, v0
	s_waitcnt lgkmcnt(2)
	v_mfma_f32_16x16x32_f16 v[82:85], v[46:49], v[112:115], v[82:85]
	ds_read_b64_tr_b16 v[112:113], v121
	v_add_u32_e32 v123, 0x1e060, v0
	v_add_u32_e32 v117, 0x17620, v0
	s_waitcnt lgkmcnt(1)
	v_mfma_f32_16x16x32_f16 v[82:85], v[42:45], v[86:89], v[82:85]
	ds_read_b64_tr_b16 v[114:115], v122
	ds_read_b64_tr_b16 v[86:87], v116
	ds_read_b64_tr_b16 v[88:89], v123
	v_add_u32_e32 v118, 0x17a60, v0
	v_add_u32_e32 v116, 0x1fe20, v0
	s_waitcnt lgkmcnt(2)
	v_mfma_f32_16x16x32_f16 v[82:85], v[38:41], v[112:115], v[82:85]
	ds_read_b64_tr_b16 v[112:113], v117
	v_add_u32_e32 v0, 0x20260, v0
	s_add_i32 s1, s1, 64
	s_waitcnt lgkmcnt(1)
	v_mfma_f32_16x16x32_f16 v[82:85], v[34:37], v[86:89], v[82:85]
	ds_read_b64_tr_b16 v[114:115], v118
	ds_read_b64_tr_b16 v[86:87], v116
	ds_read_b64_tr_b16 v[88:89], v0
	s_cmpk_eq_i32 s1, 0x100
	s_waitcnt lgkmcnt(2)
	v_mfma_f32_16x16x32_f16 v[82:85], v[30:33], v[112:115], v[82:85]
	s_waitcnt lgkmcnt(0)
	v_mfma_f32_16x16x32_f16 v[82:85], v[26:29], v[86:89], v[82:85]
	s_nop 7
	v_cvt_f16_f32_e32 v0, v82
	v_cvt_f16_f32_e32 v82, v83
	v_cvt_f16_f32_e32 v83, v84
	v_cvt_f16_f32_e32 v84, v85
	ds_write_b16 v111, v0 offset:32
	ds_write_b16 v111, v82 offset:288
	ds_write_b16 v111, v83 offset:544
	ds_write_b16 v111, v84 offset:800
	s_cbranch_scc0 .LBB0_557
	s_ashr_i32 s39, s38, 31
	s_mul_i32 s26, s19, 0xc000
	s_lshl_b64 s[20:21], s[38:39], 1
	s_lshl_b64 s[24:25], s[26:27], 1
	s_add_u32 s1, s42, s24
	s_addc_u32 s10, s43, s25
	s_add_u32 s48, s1, s20
	v_lshl_add_u64 v[82:83], v[98:99], 0, s[20:21]
	s_addc_u32 s49, s10, s21
	s_mov_b64 s[38:39], -1
	s_and_b64 vcc, exec, s[16:17]
	s_waitcnt lgkmcnt(0)
	s_barrier
	s_cbranch_vccz .LBB0_560
	ds_read_b128 v[84:87], v206
	v_add_u32_e32 v0, s19, v176
	v_mad_i64_i32 v[88:89], s[20:21], v0, s8, v[82:83]
	s_mov_b64 s[38:39], 0
	s_waitcnt lgkmcnt(0)
	global_store_dwordx4 v[88:89], v[84:87], off
